# v93 + V-transpose task: rows 8..51 of the tile touched up front with dummy-destination loads so the 7 later serialized 8-load groups hit in cache
# speedup vs baseline: 1.0118x; 1.0034x over previous
.LBB0_501:
	s_andn2_saveexec_b64 s[2:3], s[16:17]
	s_cbranch_execz .LBB0_530
	v_add_u32_e32 v4, 0xffffff00, v81
	s_mov_b32 s0, 0xe38f
	v_mul_u32_u24_sdwa v1, v4, s0 dst_sel:DWORD dst_unused:UNUSED_PAD src0_sel:WORD_0 src1_sel:DWORD
	v_lshrrev_b32_e32 v2, 21, v1
	v_mul_lo_u16_e32 v3, 36, v2
	v_sub_u16_e32 v3, v4, v3
	v_mov_b32_e32 v0, v236
	v_lshrrev_b32_e32 v5, 22, v1
	v_cmp_lt_u16_e32 vcc, 31, v3
	v_lshlrev_b16_e32 v3, 6, v3
	s_and_saveexec_b64 s[0:1], vcc
	s_xor_b64 s[0:1], exec, s[0:1]
	v_lshlrev_b32_e32 v1, 8, v5
	s_movk_i32 s4, 0x3800
	v_add3_u32 v1, v3, v1, s4
	s_andn2_saveexec_b64 s[0:1], s[0:1]
	v_lshl_or_b32 v1, v5, 11, v3
	s_or_b64 exec, exec, s[0:1]
	v_readlane_b32 s8, v254, 28
	v_readlane_b32 s9, v254, 29
	s_movk_i32 s6, 0x1200
	v_lshlrev_b32_e32 v8, 7, v2
	v_mov_b64_e32 v[6:7], s[8:9]
	v_and_b32_e32 v5, 63, v0
	v_mad_u64_u32 v[0:1], s[0:1], v1, s6, v[6:7]
	v_and_b32_e32 v160, 0x80, v8
	v_lshl_add_u64 v[0:1], v[0:1], 0, v[160:161]
	v_lshlrev_b32_e32 v160, 1, v5
	v_lshl_add_u64 v[0:1], v[0:1], 0, v[160:161]
	s_mov_b32 s0, 0xb200000
	v_add_co_u32_e32 v8, vcc, s0, v0
	s_mov_b32 s0, 0xb201000
	s_nop 0
	v_addc_co_u32_e32 v9, vcc, 0, v1, vcc
	v_add_co_u32_e32 v10, vcc, s0, v0
	s_mov_b32 s0, 0xb202000
	s_nop 0
	v_addc_co_u32_e32 v11, vcc, 0, v1, vcc
	v_add_co_u32_e32 v12, vcc, s0, v0
	s_mov_b32 s0, 0xb203000
	s_nop 0
	v_addc_co_u32_e32 v13, vcc, 0, v1, vcc
	v_add_co_u32_e32 v14, vcc, s0, v0
	s_mov_b32 s0, 0xb204000
	s_nop 0
	v_addc_co_u32_e32 v15, vcc, 0, v1, vcc
	v_add_co_u32_e32 v16, vcc, s0, v0
	s_mov_b32 s0, 0xb206000
	s_nop 0
	v_addc_co_u32_e32 v17, vcc, 0, v1, vcc
	v_add_co_u32_e32 v18, vcc, s0, v0
	s_mov_b32 s0, 0xb207000
	s_nop 0
	v_addc_co_u32_e32 v19, vcc, 0, v1, vcc
	v_add_co_u32_e32 v20, vcc, s0, v0
	s_mov_b32 s0, 0xb208000
	s_nop 0
	v_addc_co_u32_e32 v21, vcc, 0, v1, vcc
	v_add_co_u32_e32 v22, vcc, s0, v0
	v_lshl_or_b32 v2, v2, 6, v5
	s_nop 0
	v_addc_co_u32_e32 v23, vcc, 0, v1, vcc
	global_load_ushort v8, v[8:9], off offset:1792
	s_nop 0
	global_load_ushort v9, v[10:11], off offset:2304
	global_load_ushort v24, v[12:13], off offset:2816
	global_load_ushort v25, v[14:15], off offset:3328
	global_load_ushort v26, v[16:17], off offset:3840
	global_load_ushort v27, v[18:19], off offset:256
	global_load_ushort v28, v[20:21], off offset:768
	global_load_ushort v29, v[22:23], off offset:1280
	s_mov_b32 s98, 0xb209700
	s_mov_b32 s99, 0
	v_lshl_add_u64 v[250:251], v[0:1], 0, s[98:99]
	s_movk_i32 s98, 0x1200
	s_nop 0
	global_load_ushort v196, v[250:251], off
	v_lshl_add_u64 v[250:251], v[250:251], 0, s[98:99]
	s_nop 0
	global_load_ushort v197, v[250:251], off
	v_lshl_add_u64 v[250:251], v[250:251], 0, s[98:99]
	s_nop 0
	global_load_ushort v198, v[250:251], off
	v_lshl_add_u64 v[250:251], v[250:251], 0, s[98:99]
	s_nop 0
	global_load_ushort v199, v[250:251], off
	v_lshl_add_u64 v[250:251], v[250:251], 0, s[98:99]
	s_nop 0
	global_load_ushort v200, v[250:251], off
	v_lshl_add_u64 v[250:251], v[250:251], 0, s[98:99]
	s_nop 0
	global_load_ushort v201, v[250:251], off
	v_lshl_add_u64 v[250:251], v[250:251], 0, s[98:99]
	s_nop 0
	global_load_ushort v202, v[250:251], off
	v_lshl_add_u64 v[250:251], v[250:251], 0, s[98:99]
	s_nop 0
	global_load_ushort v203, v[250:251], off
	v_lshl_add_u64 v[250:251], v[250:251], 0, s[98:99]
	s_nop 0
	global_load_ushort v206, v[250:251], off
	v_lshl_add_u64 v[250:251], v[250:251], 0, s[98:99]
	s_nop 0
	global_load_ushort v207, v[250:251], off
	v_lshl_add_u64 v[250:251], v[250:251], 0, s[98:99]
	s_nop 0
	global_load_ushort v208, v[250:251], off
	v_lshl_add_u64 v[250:251], v[250:251], 0, s[98:99]
	s_nop 0
	global_load_ushort v209, v[250:251], off
	v_lshl_add_u64 v[250:251], v[250:251], 0, s[98:99]
	s_nop 0
	global_load_ushort v210, v[250:251], off
	v_lshl_add_u64 v[250:251], v[250:251], 0, s[98:99]
	s_nop 0
	global_load_ushort v211, v[250:251], off
	v_lshl_add_u64 v[250:251], v[250:251], 0, s[98:99]
	s_nop 0
	global_load_ushort v212, v[250:251], off
	v_lshl_add_u64 v[250:251], v[250:251], 0, s[98:99]
	s_nop 0
	global_load_ushort v213, v[250:251], off
	v_lshl_add_u64 v[250:251], v[250:251], 0, s[98:99]
	s_nop 0
	global_load_ushort v214, v[250:251], off
	v_lshl_add_u64 v[250:251], v[250:251], 0, s[98:99]
	s_nop 0
	global_load_ushort v215, v[250:251], off
	v_lshl_add_u64 v[250:251], v[250:251], 0, s[98:99]
	s_nop 0
	global_load_ushort v216, v[250:251], off
	v_lshl_add_u64 v[250:251], v[250:251], 0, s[98:99]
	s_nop 0
	global_load_ushort v217, v[250:251], off
	v_lshl_add_u64 v[250:251], v[250:251], 0, s[98:99]
	s_nop 0
	global_load_ushort v218, v[250:251], off
	v_lshl_add_u64 v[250:251], v[250:251], 0, s[98:99]
	s_nop 0
	global_load_ushort v219, v[250:251], off
	v_lshl_add_u64 v[250:251], v[250:251], 0, s[98:99]
	s_nop 0
	global_load_ushort v220, v[250:251], off
	v_lshl_add_u64 v[250:251], v[250:251], 0, s[98:99]
	s_nop 0
	global_load_ushort v221, v[250:251], off
	v_lshl_add_u64 v[250:251], v[250:251], 0, s[98:99]
	s_nop 0
	global_load_ushort v222, v[250:251], off
	v_lshl_add_u64 v[250:251], v[250:251], 0, s[98:99]
	s_nop 0
	global_load_ushort v223, v[250:251], off
	v_lshl_add_u64 v[250:251], v[250:251], 0, s[98:99]
	s_nop 0
	global_load_ushort v224, v[250:251], off
	v_lshl_add_u64 v[250:251], v[250:251], 0, s[98:99]
	s_nop 0
	global_load_ushort v225, v[250:251], off
	v_lshl_add_u64 v[250:251], v[250:251], 0, s[98:99]
	s_nop 0
	global_load_ushort v226, v[250:251], off
	v_lshl_add_u64 v[250:251], v[250:251], 0, s[98:99]
	s_nop 0
	global_load_ushort v227, v[250:251], off
	v_lshl_add_u64 v[250:251], v[250:251], 0, s[98:99]
	s_nop 0
	global_load_ushort v228, v[250:251], off
	v_lshl_add_u64 v[250:251], v[250:251], 0, s[98:99]
	s_nop 0
	global_load_ushort v229, v[250:251], off
	v_lshl_add_u64 v[250:251], v[250:251], 0, s[98:99]
	s_nop 0
	global_load_ushort v230, v[250:251], off
	v_lshl_add_u64 v[250:251], v[250:251], 0, s[98:99]
	s_nop 0
	global_load_ushort v231, v[250:251], off
	v_lshl_add_u64 v[250:251], v[250:251], 0, s[98:99]
	s_nop 0
	global_load_ushort v232, v[250:251], off
	v_lshl_add_u64 v[250:251], v[250:251], 0, s[98:99]
	s_nop 0
	global_load_ushort v233, v[250:251], off
	v_lshl_add_u64 v[250:251], v[250:251], 0, s[98:99]
	s_nop 0
	global_load_ushort v234, v[250:251], off
	v_lshl_add_u64 v[250:251], v[250:251], 0, s[98:99]
	s_nop 0
	global_load_ushort v235, v[250:251], off
	v_lshl_add_u64 v[250:251], v[250:251], 0, s[98:99]
	s_nop 0
	global_load_ushort v240, v[250:251], off
	v_lshl_add_u64 v[250:251], v[250:251], 0, s[98:99]
	s_nop 0
	global_load_ushort v241, v[250:251], off
	v_lshl_add_u64 v[250:251], v[250:251], 0, s[98:99]
	s_nop 0
	global_load_ushort v242, v[250:251], off
	v_lshl_add_u64 v[250:251], v[250:251], 0, s[98:99]
	s_nop 0
	global_load_ushort v243, v[250:251], off
	v_lshl_add_u64 v[250:251], v[250:251], 0, s[98:99]
	s_nop 0
	global_load_ushort v248, v[250:251], off
	v_lshl_add_u64 v[250:251], v[250:251], 0, s[98:99]
	s_nop 0
	global_load_ushort v249, v[250:251], off
	v_lshl_add_u64 v[250:251], v[250:251], 0, s[98:99]
	v_mad_u64_u32 v[6:7], s[0:1], v2, s6, v[6:7]
	s_mov_b32 s0, 0xb209000
	s_nop 0
	v_add_co_u32_e32 v10, vcc, s0, v0
	s_mov_b32 s0, 0xb20a000
	s_nop 0
	v_addc_co_u32_e32 v11, vcc, 0, v1, vcc
	v_add_co_u32_e32 v12, vcc, s0, v0
	s_mov_b32 s0, 0xb20b000
	s_nop 0
	v_addc_co_u32_e32 v13, vcc, 0, v1, vcc
	v_add_co_u32_e32 v14, vcc, s0, v0
	s_mov_b32 s0, 0xb20c000
	s_nop 0
	v_addc_co_u32_e32 v15, vcc, 0, v1, vcc
	v_add_co_u32_e32 v16, vcc, s0, v0
	s_mov_b32 s0, 0xb20d000
	s_nop 0
	v_addc_co_u32_e32 v17, vcc, 0, v1, vcc
	v_add_co_u32_e32 v18, vcc, s0, v0
	s_mov_b32 s0, 0xb20f000
	s_nop 0
	v_addc_co_u32_e32 v19, vcc, 0, v1, vcc
	v_lshlrev_b32_e32 v160, 1, v3
	v_add_co_u32_e32 v20, vcc, s0, v0
	v_lshl_add_u64 v[2:3], v[6:7], 0, v[160:161]
	s_nop 0
	v_addc_co_u32_e32 v21, vcc, 0, v1, vcc
	s_mov_b32 s0, 0x19300000
	v_add_co_u32_e32 v22, vcc, s0, v2
	s_mov_b32 s0, 0xb210000
	s_nop 0
	v_addc_co_u32_e32 v23, vcc, 0, v3, vcc
	v_readlane_b32 s10, v255, 11
	v_readlane_b32 s11, v255, 12
	v_mov_b32_e32 v60, 0
	s_mov_b32 s14, 0
	v_mov_b32_e32 v38, 0
	v_mov_b32_e32 v39, v60
	v_mov_b32_e32 v36, 0
	v_mov_b32_e32 v37, v60
	s_waitcnt vmcnt(0)
	v_lshl_or_b32 v6, v9, 16, v8
	v_lshl_or_b32 v7, v25, 16, v24
	v_lshl_or_b32 v8, v27, 16, v26
	v_lshl_or_b32 v9, v29, 16, v28
	global_store_dwordx4 v[22:23], v[6:9], off
	s_nop 1
	v_add_co_u32_e32 v6, vcc, s0, v0
	s_mov_b32 s0, 0xb211000
	s_nop 0
	v_addc_co_u32_e32 v7, vcc, 0, v1, vcc
	v_add_co_u32_e32 v8, vcc, s0, v0
	s_mov_b32 s0, 0xb212000
	s_nop 0
	v_addc_co_u32_e32 v9, vcc, 0, v1, vcc
	global_load_ushort v5, v[10:11], off offset:1792
	global_load_ushort v26, v[12:13], off offset:2304
	global_load_ushort v27, v[14:15], off offset:2816
	global_load_ushort v28, v[16:17], off offset:3328
	global_load_ushort v29, v[18:19], off offset:3840
	global_load_ushort v30, v[20:21], off offset:256
	global_load_ushort v31, v[6:7], off offset:768
	s_nop 0
	global_load_ushort v9, v[8:9], off offset:1280
	v_add_co_u32_e32 v10, vcc, s0, v0
	s_mov_b32 s0, 0xb213000
	s_nop 0
	v_addc_co_u32_e32 v11, vcc, 0, v1, vcc
	v_add_co_u32_e32 v12, vcc, s0, v0
	s_mov_b32 s0, 0xb214000
	s_nop 0
	v_addc_co_u32_e32 v13, vcc, 0, v1, vcc
	v_add_co_u32_e32 v14, vcc, s0, v0
	s_mov_b32 s0, 0xb215000
	s_nop 0
	v_addc_co_u32_e32 v15, vcc, 0, v1, vcc
	v_add_co_u32_e32 v16, vcc, s0, v0
	s_mov_b32 s0, 0xb216000
	s_nop 0
	v_addc_co_u32_e32 v17, vcc, 0, v1, vcc
	v_add_co_u32_e32 v18, vcc, s0, v0
	s_mov_b32 s0, 0xb218000
	s_nop 0
	v_addc_co_u32_e32 v19, vcc, 0, v1, vcc
	v_add_co_u32_e32 v20, vcc, s0, v0
	s_mov_b32 s0, 0xb219000
	s_nop 0
	v_addc_co_u32_e32 v21, vcc, 0, v1, vcc
	v_add_co_u32_e32 v22, vcc, s0, v0
	s_mov_b32 s0, 0xb21a000
	s_nop 0
	v_addc_co_u32_e32 v23, vcc, 0, v1, vcc
	v_add_co_u32_e32 v24, vcc, s0, v0
	s_mov_b64 s[0:1], 0x19300000
	v_lshl_add_u64 v[2:3], v[2:3], 0, s[0:1]
	v_addc_co_u32_e32 v25, vcc, 0, v1, vcc
	s_mov_b32 s0, 0xb21b000
	s_waitcnt vmcnt(0)
	v_lshl_or_b32 v6, v26, 16, v5
	v_lshl_or_b32 v7, v28, 16, v27
	v_lshl_or_b32 v8, v30, 16, v29
	v_lshl_or_b32 v9, v9, 16, v31
	global_store_dwordx4 v[2:3], v[6:9], off offset:16
	global_load_ushort v5, v[10:11], off offset:1792
	s_nop 0
	global_load_ushort v6, v[12:13], off offset:2304
	global_load_ushort v7, v[14:15], off offset:2816
	global_load_ushort v8, v[16:17], off offset:3328
	global_load_ushort v9, v[18:19], off offset:3840
	global_load_ushort v26, v[20:21], off offset:256
	global_load_ushort v27, v[22:23], off offset:768
	global_load_ushort v28, v[24:25], off offset:1280
	v_add_co_u32_e32 v10, vcc, s0, v0
	s_mov_b32 s0, 0xb21c000
	s_nop 0
	v_addc_co_u32_e32 v11, vcc, 0, v1, vcc
	v_add_co_u32_e32 v12, vcc, s0, v0
	s_mov_b32 s0, 0xb21d000
	s_nop 0
	v_addc_co_u32_e32 v13, vcc, 0, v1, vcc
	v_add_co_u32_e32 v14, vcc, s0, v0
	s_mov_b32 s0, 0xb21e000
	s_nop 0
	v_addc_co_u32_e32 v15, vcc, 0, v1, vcc
	v_add_co_u32_e32 v16, vcc, s0, v0
	s_mov_b32 s0, 0xb21f000
	s_nop 0
	v_addc_co_u32_e32 v17, vcc, 0, v1, vcc
	v_add_co_u32_e32 v18, vcc, s0, v0
	s_mov_b32 s0, 0xb221000
	s_nop 0
	v_addc_co_u32_e32 v19, vcc, 0, v1, vcc
	v_add_co_u32_e32 v20, vcc, s0, v0
	s_mov_b32 s0, 0xb222000
	s_nop 0
	v_addc_co_u32_e32 v21, vcc, 0, v1, vcc
	v_add_co_u32_e32 v22, vcc, s0, v0
	s_mov_b32 s0, 0xb223000
	s_nop 0
	v_addc_co_u32_e32 v23, vcc, 0, v1, vcc
	v_add_co_u32_e32 v24, vcc, s0, v0
	s_mov_b32 s0, 0xb224000
	s_nop 0
	v_addc_co_u32_e32 v25, vcc, 0, v1, vcc
	s_waitcnt vmcnt(0)
	v_lshl_or_b32 v6, v6, 16, v5
	v_lshl_or_b32 v7, v8, 16, v7
	v_lshl_or_b32 v8, v26, 16, v9
	v_lshl_or_b32 v9, v28, 16, v27
	global_store_dwordx4 v[2:3], v[6:9], off offset:32
	global_load_ushort v5, v[10:11], off offset:1792
	s_nop 0
	global_load_ushort v6, v[12:13], off offset:2304
	global_load_ushort v7, v[14:15], off offset:2816
	global_load_ushort v8, v[16:17], off offset:3328
	global_load_ushort v9, v[18:19], off offset:3840
	global_load_ushort v26, v[20:21], off offset:256
	global_load_ushort v27, v[22:23], off offset:768
	global_load_ushort v28, v[24:25], off offset:1280
	v_add_co_u32_e32 v10, vcc, s0, v0
	s_mov_b32 s0, 0xb225000
	s_nop 0
	v_addc_co_u32_e32 v11, vcc, 0, v1, vcc
	v_add_co_u32_e32 v12, vcc, s0, v0
	s_mov_b32 s0, 0xb226000
	s_nop 0
	v_addc_co_u32_e32 v13, vcc, 0, v1, vcc
	v_add_co_u32_e32 v14, vcc, s0, v0
	s_mov_b32 s0, 0xb227000
	s_nop 0
	v_addc_co_u32_e32 v15, vcc, 0, v1, vcc
	v_add_co_u32_e32 v16, vcc, s0, v0
	s_mov_b32 s0, 0xb228000
	s_nop 0
	v_addc_co_u32_e32 v17, vcc, 0, v1, vcc
	v_add_co_u32_e32 v18, vcc, s0, v0
	s_mov_b32 s0, 0xb22a000
	s_nop 0
	v_addc_co_u32_e32 v19, vcc, 0, v1, vcc
	v_add_co_u32_e32 v20, vcc, s0, v0
	s_mov_b32 s0, 0xb22b000
	s_nop 0
	v_addc_co_u32_e32 v21, vcc, 0, v1, vcc
	v_add_co_u32_e32 v22, vcc, s0, v0
	s_mov_b32 s0, 0xb22c000
	s_nop 0
	v_addc_co_u32_e32 v23, vcc, 0, v1, vcc
	v_add_co_u32_e32 v24, vcc, s0, v0
	s_mov_b32 s0, 0xb22d000
	s_nop 0
	v_addc_co_u32_e32 v25, vcc, 0, v1, vcc
	s_waitcnt vmcnt(0)
	v_lshl_or_b32 v6, v6, 16, v5
	v_lshl_or_b32 v7, v8, 16, v7
	v_lshl_or_b32 v8, v26, 16, v9
	v_lshl_or_b32 v9, v28, 16, v27
	global_store_dwordx4 v[2:3], v[6:9], off offset:48
	global_load_ushort v5, v[10:11], off offset:1792
	s_nop 0
	global_load_ushort v6, v[12:13], off offset:2304
	global_load_ushort v7, v[14:15], off offset:2816
	global_load_ushort v8, v[16:17], off offset:3328
	global_load_ushort v9, v[18:19], off offset:3840
	global_load_ushort v26, v[20:21], off offset:256
	global_load_ushort v27, v[22:23], off offset:768
	global_load_ushort v28, v[24:25], off offset:1280
	v_add_co_u32_e32 v10, vcc, s0, v0
	s_mov_b32 s0, 0xb22e000
	s_nop 0
	v_addc_co_u32_e32 v11, vcc, 0, v1, vcc
	v_add_co_u32_e32 v12, vcc, s0, v0
	s_mov_b32 s0, 0xb22f000
	s_nop 0
	v_addc_co_u32_e32 v13, vcc, 0, v1, vcc
	v_add_co_u32_e32 v14, vcc, s0, v0
	s_mov_b32 s0, 0xb230000
	s_nop 0
	v_addc_co_u32_e32 v15, vcc, 0, v1, vcc
	v_add_co_u32_e32 v16, vcc, s0, v0
	s_mov_b32 s0, 0xb231000
	s_nop 0
	v_addc_co_u32_e32 v17, vcc, 0, v1, vcc
	v_add_co_u32_e32 v18, vcc, s0, v0
	s_mov_b32 s0, 0xb233000
	s_nop 0
	v_addc_co_u32_e32 v19, vcc, 0, v1, vcc
	v_add_co_u32_e32 v20, vcc, s0, v0
	s_mov_b32 s0, 0xb234000
	s_nop 0
	v_addc_co_u32_e32 v21, vcc, 0, v1, vcc
	v_add_co_u32_e32 v22, vcc, s0, v0
	s_mov_b32 s0, 0xb235000
	s_nop 0
	v_addc_co_u32_e32 v23, vcc, 0, v1, vcc
	v_add_co_u32_e32 v24, vcc, s0, v0
	s_mov_b32 s0, 0xb236000
	s_nop 0
	v_addc_co_u32_e32 v25, vcc, 0, v1, vcc
	s_waitcnt vmcnt(0)
	v_lshl_or_b32 v6, v6, 16, v5
	v_lshl_or_b32 v7, v8, 16, v7
	v_lshl_or_b32 v8, v26, 16, v9
	v_lshl_or_b32 v9, v28, 16, v27
	global_store_dwordx4 v[2:3], v[6:9], off offset:64
	global_load_ushort v5, v[10:11], off offset:1792
	s_nop 0
	global_load_ushort v6, v[12:13], off offset:2304
	global_load_ushort v7, v[14:15], off offset:2816
	global_load_ushort v8, v[16:17], off offset:3328
	global_load_ushort v9, v[18:19], off offset:3840
	global_load_ushort v26, v[20:21], off offset:256
	global_load_ushort v27, v[22:23], off offset:768
	global_load_ushort v28, v[24:25], off offset:1280
	v_add_co_u32_e32 v10, vcc, s0, v0
	s_mov_b32 s0, 0xb237000
	s_nop 0
	v_addc_co_u32_e32 v11, vcc, 0, v1, vcc
	v_add_co_u32_e32 v12, vcc, s0, v0
	s_mov_b32 s0, 0xb238000
	s_nop 0
	v_addc_co_u32_e32 v13, vcc, 0, v1, vcc
	v_add_co_u32_e32 v14, vcc, s0, v0
	s_mov_b32 s0, 0xb239000
	s_nop 0
	v_addc_co_u32_e32 v15, vcc, 0, v1, vcc
	v_add_co_u32_e32 v16, vcc, s0, v0
	s_mov_b32 s0, 0xb23a000
	s_nop 0
	v_addc_co_u32_e32 v17, vcc, 0, v1, vcc
	v_add_co_u32_e32 v18, vcc, s0, v0
	s_mov_b32 s0, 0xb23c000
	s_nop 0
	v_addc_co_u32_e32 v19, vcc, 0, v1, vcc
	v_add_co_u32_e32 v20, vcc, s0, v0
	s_mov_b32 s0, 0xb23d000
	s_nop 0
	v_addc_co_u32_e32 v21, vcc, 0, v1, vcc
	v_add_co_u32_e32 v22, vcc, s0, v0
	s_mov_b32 s0, 0xb23e000
	s_nop 0
	v_addc_co_u32_e32 v23, vcc, 0, v1, vcc
	v_add_co_u32_e32 v24, vcc, s0, v0
	s_mov_b32 s0, 0xb23f000
	s_nop 0
	v_addc_co_u32_e32 v25, vcc, 0, v1, vcc
	s_waitcnt vmcnt(0)
	v_lshl_or_b32 v6, v6, 16, v5
	v_lshl_or_b32 v7, v8, 16, v7
	v_lshl_or_b32 v8, v26, 16, v9
	v_lshl_or_b32 v9, v28, 16, v27
	global_store_dwordx4 v[2:3], v[6:9], off offset:80
	global_load_ushort v5, v[10:11], off offset:1792
	s_nop 0
	global_load_ushort v6, v[12:13], off offset:2304
	global_load_ushort v7, v[14:15], off offset:2816
	global_load_ushort v8, v[16:17], off offset:3328
	global_load_ushort v9, v[18:19], off offset:3840
	global_load_ushort v26, v[20:21], off offset:256
	global_load_ushort v27, v[22:23], off offset:768
	s_nop 0
	global_load_ushort v24, v[24:25], off offset:1280
	v_add_co_u32_e32 v10, vcc, s0, v0
	s_mov_b32 s0, 0xb240000
	s_nop 0
	v_addc_co_u32_e32 v11, vcc, 0, v1, vcc
	v_add_co_u32_e32 v12, vcc, s0, v0
	s_mov_b32 s0, 0xb241000
	s_nop 0
	v_addc_co_u32_e32 v13, vcc, 0, v1, vcc
	v_add_co_u32_e32 v14, vcc, s0, v0
	s_mov_b32 s0, 0xb242000
	s_nop 0
	v_addc_co_u32_e32 v15, vcc, 0, v1, vcc
	v_add_co_u32_e32 v16, vcc, s0, v0
	s_mov_b32 s0, 0xb243000
	s_nop 0
	v_addc_co_u32_e32 v17, vcc, 0, v1, vcc
	v_add_co_u32_e32 v18, vcc, s0, v0
	s_mov_b32 s0, 0xb245000
	s_nop 0
	v_addc_co_u32_e32 v19, vcc, 0, v1, vcc
	v_add_co_u32_e32 v20, vcc, s0, v0
	s_mov_b32 s0, 0xb246000
	s_nop 0
	v_addc_co_u32_e32 v21, vcc, 0, v1, vcc
	v_add_co_u32_e32 v22, vcc, s0, v0
	s_mov_b32 s0, 0xb247000
	s_nop 0
	v_addc_co_u32_e32 v23, vcc, 0, v1, vcc
	v_add_co_u32_e32 v0, vcc, s0, v0
	v_readlane_b32 s0, v255, 7
	s_nop 0
	v_addc_co_u32_e32 v1, vcc, 0, v1, vcc
	v_readlane_b32 s1, v255, 8
	s_lshl_b64 s[0:1], s[0:1], 2
	s_add_u32 s0, s8, s0
	s_addc_u32 s1, s9, s1
	s_waitcnt vmcnt(0)
	v_lshl_or_b32 v6, v6, 16, v5
	v_lshl_or_b32 v7, v8, 16, v7
	v_lshl_or_b32 v8, v26, 16, v9
	v_lshl_or_b32 v9, v24, 16, v27
	global_store_dwordx4 v[2:3], v[6:9], off offset:96
	global_load_ushort v5, v[10:11], off offset:1792
	s_nop 0
	global_load_ushort v6, v[12:13], off offset:2304
	global_load_ushort v7, v[14:15], off offset:2816
	global_load_ushort v10, v[16:17], off offset:3328
	global_load_ushort v11, v[18:19], off offset:3840
	s_nop 0
	global_load_ushort v12, v[20:21], off offset:256
	global_load_ushort v13, v[22:23], off offset:768
	global_load_ushort v14, v[0:1], off offset:1280
	v_mov_b32_e32 v0, 0x300
	v_lshl_add_u32 v54, v4, 3, v0
	v_mov_b32_e32 v15, v236
	v_mov_b64_e32 v[0:1], s[10:11]
	v_mad_u64_u32 v[8:9], s[4:5], v54, s6, v[0:1]
	s_waitcnt vmcnt(0)
	v_lshl_or_b32 v4, v6, 16, v5
	v_lshl_or_b32 v5, v10, 16, v7
	v_lshl_or_b32 v6, v12, 16, v11
	v_lshl_or_b32 v7, v14, 16, v13
	global_store_dwordx4 v[2:3], v[4:7], off offset:112
	s_nop 0
	v_and_b32_e32 v14, 15, v15
	v_bfe_u32 v17, v15, 4, 2
	v_lshlrev_b32_e32 v19, 2, v14
	v_lshlrev_b32_e32 v2, 6, v17
	v_or_b32_e32 v21, 8, v17
	v_lshlrev_b32_e32 v160, 4, v14
	v_or_b32_e32 v23, 0x100, v19
	v_min_u32_e32 v3, 9, v21
	v_or_b32_e32 v20, v2, v19
	v_lshl_add_u64 v[0:1], s[0:1], 0, v[160:161]
	v_or_b32_e32 v16, v2, v23
	v_lshlrev_b32_e32 v24, 6, v3
	s_mov_b64 s[0:1], 0x2000
	v_lshlrev_b32_e32 v160, 1, v20
	v_lshl_add_u64 v[4:5], v[0:1], 0, s[0:1]
	v_add_co_u32_e32 v0, vcc, s20, v0
	v_lshl_add_u64 v[10:11], v[8:9], 0, v[160:161]
	v_lshlrev_b32_e32 v160, 1, v16
	v_or_b32_e32 v22, v24, v19
	v_addc_co_u32_e32 v1, vcc, 0, v1, vcc
	v_lshl_add_u64 v[12:13], v[8:9], 0, v[160:161]
	v_lshlrev_b32_e32 v160, 1, v22
	global_load_dwordx4 v[0:3], v[0:1], off
	s_nop 0
	global_load_dwordx4 v[4:7], v[4:5], off offset:1024
	v_lshl_add_u64 v[8:9], v[8:9], 0, v[160:161]
	global_load_dwordx2 v[42:43], v[10:11], off offset:512
	global_load_dwordx2 v[40:41], v[12:13], off offset:512
	global_load_dwordx2 v[34:35], v[8:9], off offset:512
	v_and_b32_e32 v8, 63, v15
	v_and_b32_e32 v9, 4, v15
	v_lshlrev_b32_e32 v160, 3, v8
	v_cmp_eq_u32_e64 s[36:37], 0, v9
	v_cmp_gt_u32_e64 s[38:39], 8, v14
	v_and_b32_e32 v14, 12, v19
	v_lshl_add_u64 v[8:9], s[8:9], 0, v[160:161]
	s_mov_b64 s[0:1], 0x16f00000
	v_lshl_add_u64 v[12:13], v[8:9], 0, s[0:1]
	v_cvt_f32_ubyte0_e32 v8, v14
	v_mul_f32_e32 v8, 0xbf549a78, v8
	v_exp_f32_e32 v56, v8
	v_or_b32_e32 v8, 1, v14
	v_cvt_f32_ubyte0_e32 v8, v8
	v_mul_f32_e32 v8, 0xbf549a78, v8
	v_exp_f32_e32 v57, v8
	v_or_b32_e32 v8, 2, v14
	v_cvt_f32_ubyte0_e32 v8, v8
	v_mul_f32_e32 v8, 0xbf549a78, v8
	v_exp_f32_e32 v58, v8
	v_or_b32_e32 v8, 3, v14
	v_cvt_f32_ubyte0_e32 v8, v8
	v_mul_f32_e32 v8, 0xbf549a78, v8
	v_exp_f32_e32 v59, v8
	v_mad_i64_i32 v[8:9], s[0:1], v54, s6, 0
	v_add_u32_e32 v18, 0x100, v16
	v_or_b32_e32 v24, v24, v23
	v_or_b32_e32 v8, v8, v160
	v_cmp_gt_u32_e32 vcc, 10, v21
	v_lshlrev_b32_e64 v55, v17, 1
	v_lshl_add_u64 v[10:11], s[10:11], 0, v[160:161]
	v_lshl_add_u64 v[14:15], s[10:11], 0, v[8:9]
	v_lshlrev_b32_e32 v8, 1, v16
	v_lshlrev_b32_e32 v16, 1, v18
	v_lshlrev_b32_e32 v18, 1, v24
	v_lshlrev_b32_e32 v20, 1, v20
	v_lshlrev_b32_e32 v22, 1, v22
	v_mov_b32_e32 v21, 0
	s_branch .LBB0_508
